# attention unit prologue: Q loads issued right behind the K0 DMA so the first wait covers K0+Q only (V0/K1/K2 stay in flight through step 0); Q ladder waits dropped
# speedup vs baseline: 1.0124x; 1.0124x over previous
; #define WAIT_BAR(N) asm volatile("s_waitcnt vmcnt(" #N ") lgkmcnt(0)\n\ts_barrier":::"memory")
;   #define DMA_K(t,slot) glds16(ksrc+(long)(t)*KVBLK*DM,(unsigned)__builtin_amdgcn_readfirstlane(kdst+(slot)))
;   #define DMA_V(t,slot) do{ glds16(vsrc+(long)(t)*KVBLK*DM,(unsigned)__builtin_amdgcn_readfirstlane(vdst+2*(slot))); glds16(vsrc+(long)(t)*KVBLK*DM+64,(unsigned)__builtin_amdgcn_readfirstlane(vdst+2*(slot)+8192)); }while(0)
;   #define CMASK(P0,P1,t) do{int jb_=(t)-(NT-4); if(jb_>=0)cmask(P0,P1,jb_,qrel,hi);}while(0)
;   #define CMASK(P0,P1,t) do{}while(0)
;   #define CMASK(P0,P1,t) do{int jb_=(t)-(NT-4); if(jb_>=0)cmask(P0,P1,jb_,qrel,hi);}while(0)
; template<int THRL> __device__ __forceinline__ void attn_unit(int b,int hq,int vcol,int qb,const bf16*Q,const bf16*__restrict__ K,const bf16*__restrict__ V,bf16*O,char*shm){
;     ...
;   const int vb0=(int)(lds0+LDS_V)+((lane>>4)&1)*32+(lane&3)*8+(4*hi+((lane&15)>>2))*64;
;   const char*Kbase=shm+LDS_K; bf16x8 kf[8];
;   const lds_cptr shm3=(lds_cptr)shm; const lds_cptr kp0=shm3+LDS_K+hi*1024+r32*16; const lds_cptr vp0=shm3+LDS_V+((lane>>4)&1)*32+(lane&3)*8+(4*hi+((lane&15)>>2))*64;
;   const int NT=(q0+QB)/KVBLK;
;   DMA_K(0,0);DMA_V(0,0);DMA_K(1,SLOTB);
;   bf16x8 qr[4];
;   #pragma unroll
;   for(int d0=0;d0<4;++d0)qr[d0]=*reinterpret_cast<const bf16x8*>(&Qw[(long)r32*DM+d0*16+hi*8]);
;   float mhat=0.f,l_reg=0.f;f32x16 o[4];o[0]=f32x16{};o[1]=f32x16{};o[2]=f32x16{};o[3]=f32x16{};f32x16 negm=f32x16{};asm volatile("":"+v"(negm));
;   const int qrel=wid*QBLK+r32;
;     ...
;   bool resc=false;
;     ...
;   f32x16 pA0,pA1,pB0,pB1;
;   int sl_prev=0,sl_cur=0,sl_next=SLOTB;
;     ...
;   DMA_K(2,2*SLOTB);
;   WAIT_BAR(4);
;   qkt(pA0,pA1,Kbase,qr,negm,r32,hi);asm volatile("s_nop 15\n\ts_nop 7":"+v"(pA0),"+v"(pA1));CMASK(pA0,pA1,0);
.LBB0_258:
	v_mov_b32_e32 v36, v244
	s_mov_b32 s50, s92
	v_readfirstlane_b32 s33, v36
	s_ashr_i32 s65, s33, 6
	s_lshl_b32 s2, s65, 5
	s_ashr_i32 s3, s2, 31
	s_add_u32 s40, s2, s82
	s_addc_u32 s41, s3, 0
	s_lshl_b64 s[2:3], s[40:41], 11
	s_add_u32 s12, s6, s2
	s_addc_u32 s22, s7, s3
	s_or_b32 s90, s4, s79
	s_lshl_b64 s[2:3], s[90:91], 1
	s_add_u32 s24, s12, s2
	s_addc_u32 s25, s22, s3
	v_and_b32_e32 v250, 63, v36
	s_add_u32 s2, s83, s2
	s_addc_u32 s3, s1, s3
	v_lshlrev_b32_e32 v0, 11, v250
	v_lshl_add_u64 v[2:3], s[2:3], 0, v[0:1]
	s_lshl_b32 s2, s65, 3
	s_ashr_i32 s3, s2, 31
	v_lshl_add_u64 v[238:239], s[2:3], 1, v[2:3]
	s_lshl_b32 s2, s65, 4
	v_bfe_u32 v228, v36, 2, 4
	v_and_or_b32 v0, s2, 48, v228
	s_ashr_i32 s2, s33, 3
	s_and_b32 s92, s2, 0xffffffe0
	s_ashr_i32 s93, s92, 31
	s_lshl_b32 s2, s65, 10
	v_lshlrev_b32_e32 v0, 11, v0
	v_lshlrev_b32_e32 v246, 3, v36
	s_cmp_lg_u32 0, -1
	v_lshl_add_u64 v[2:3], s[34:35], 0, v[0:1]
	v_and_b32_e32 v247, 24, v246
	s_cselect_b32 s3, 0, 0
	v_lshl_add_u64 v[2:3], s[92:93], 1, v[2:3]
	v_lshlrev_b32_e32 v0, 1, v247
	s_add_i32 s22, s2, s3
	s_mov_b32 m0, s22
	s_nop 0
	global_load_lds_dwordx4 v[238:239], off
	v_and_b32_e32 v251, 31, v36
	v_lshl_add_u64 v[34:35], v[2:3], 0, v[0:1]
	v_bfe_u32 v252, v36, 5, 1
	v_lshlrev_b32_e32 v0, 11, v251
	v_lshl_or_b32 v0, v252, 4, v0
	global_load_dwordx4 v[184:187], v0, s[24:25]
	global_load_dwordx4 v[176:179], v0, s[24:25] offset:32
	global_load_dwordx4 v[172:175], v0, s[24:25] offset:64
	global_load_dwordx4 v[164:167], v0, s[24:25] offset:96
	s_add_i32 s23, s22, 0x6000
	s_mov_b32 m0, s23
	s_nop 0
	global_load_lds_dwordx4 v[34:35], off
	v_lshl_add_u64 v[2:3], v[34:35], 0, s[70:71]
	s_add_i32 s3, s22, 0x8000
	s_mov_b32 m0, s3
	s_nop 0
	global_load_lds_dwordx4 v[2:3], off
	v_lshl_add_u64 v[2:3], v[238:239], 0, s[94:95]
	s_add_i32 s3, s22, 0x2000
	s_mov_b32 m0, s3
	s_nop 0
	global_load_lds_dwordx4 v[2:3], off
	v_mov_b32_e32 v2, v1
	v_mov_b32_e32 v3, v1
	v_mov_b32_e32 v4, v1
	v_mov_b32_e32 v5, v1
	v_mov_b32_e32 v6, v1
	v_mov_b32_e32 v7, v1
	v_mov_b32_e32 v8, v1
	v_mov_b32_e32 v9, v1
	v_mov_b32_e32 v10, v1
	v_mov_b32_e32 v11, v1
	v_mov_b32_e32 v12, v1
	v_mov_b32_e32 v13, v1
	v_mov_b32_e32 v14, v1
	v_mov_b32_e32 v15, v1
	v_lshlrev_b32_e32 v0, 10, v252
	v_lshlrev_b32_e32 v16, 4, v251
	v_add3_u32 v232, 0, v0, v16
	v_mov_b32_e32 v0, v1
	v_mov_b64_e32 v[16:17], v[14:15]
	v_mov_b64_e32 v[14:15], v[12:13]
	v_mov_b64_e32 v[12:13], v[10:11]
	v_mov_b64_e32 v[10:11], v[8:9]
	v_mov_b64_e32 v[8:9], v[6:7]
	v_mov_b64_e32 v[6:7], v[4:5]
	v_mov_b64_e32 v[4:5], v[2:3]
	v_mov_b64_e32 v[2:3], v[0:1]
	v_lshl_add_u64 v[18:19], v[238:239], 0, s[8:9]
	s_add_i32 s3, s22, 0x4000
	s_mov_b32 m0, s3
	s_nop 0
	global_load_lds_dwordx4 v[18:19], off
	s_waitcnt vmcnt(4) lgkmcnt(0)
	s_barrier
	ds_read_b128 v[38:41], v232
	s_andn2_b64 vcc, exec, s[42:43]
	s_waitcnt lgkmcnt(0)
	v_mfma_f32_32x32x16_bf16 v[18:33], v[38:41], v[184:187], v[2:17]
	ds_read_b128 v[38:41], v232 offset:512
	s_waitcnt lgkmcnt(0)
	v_mfma_f32_32x32x16_bf16 v[2:17], v[38:41], v[184:187], v[2:17]
	ds_read_b128 v[38:41], v232 offset:2048
	s_waitcnt lgkmcnt(0)
	v_mfma_f32_32x32x16_bf16 v[18:33], v[38:41], v[176:179], v[18:33]
	ds_read_b128 v[38:41], v232 offset:2560
	s_waitcnt lgkmcnt(0)
	v_mfma_f32_32x32x16_bf16 v[2:17], v[38:41], v[176:179], v[2:17]
	ds_read_b128 v[38:41], v232 offset:4096
	s_waitcnt lgkmcnt(0)
	v_mfma_f32_32x32x16_bf16 v[18:33], v[38:41], v[172:175], v[18:33]
	ds_read_b128 v[38:41], v232 offset:4608
	s_waitcnt lgkmcnt(0)
	v_mfma_f32_32x32x16_bf16 v[2:17], v[38:41], v[172:175], v[2:17]
	ds_read_b128 v[38:41], v232 offset:6144
	s_waitcnt lgkmcnt(0)
	v_mfma_f32_32x32x16_bf16 v[18:33], v[38:41], v[164:167], v[18:33]
	ds_read_b128 v[38:41], v232 offset:6656
	s_waitcnt lgkmcnt(0)
	v_mfma_f32_32x32x16_bf16 v[2:17], v[38:41], v[164:167], v[2:17]
	s_nop 15
	s_nop 7
	s_cbranch_vccnz .LBB0_260
	s_cmp_lt_i32 s33, 0
	s_cselect_b64 vcc, -1, 0
	s_nop 5
	v_cndmask_b32_e32 v33, v33, v248, vcc
	v_cndmask_b32_e32 v32, v32, v248, vcc
	v_cndmask_b32_e32 v31, v31, v248, vcc
	v_cndmask_b32_e32 v30, v30, v248, vcc
	v_cndmask_b32_e32 v29, v29, v248, vcc
	v_cndmask_b32_e32 v28, v28, v248, vcc
	v_cndmask_b32_e32 v27, v27, v248, vcc
	v_cndmask_b32_e32 v26, v26, v248, vcc
	v_cndmask_b32_e32 v25, v25, v248, vcc
	v_cndmask_b32_e32 v24, v24, v248, vcc
	v_cndmask_b32_e32 v23, v23, v248, vcc
	v_cndmask_b32_e32 v22, v22, v248, vcc
	v_cndmask_b32_e32 v21, v21, v248, vcc
	v_cndmask_b32_e32 v20, v20, v248, vcc
	v_cndmask_b32_e32 v19, v19, v248, vcc
	v_cndmask_b32_e32 v18, v18, v248, vcc
	v_cndmask_b32_e32 v17, v17, v248, vcc
	v_cndmask_b32_e32 v16, v16, v248, vcc
	v_cndmask_b32_e32 v15, v15, v248, vcc
	v_cndmask_b32_e32 v14, v14, v248, vcc
	v_cndmask_b32_e32 v13, v13, v248, vcc
	v_cndmask_b32_e32 v12, v12, v248, vcc
	v_cndmask_b32_e32 v11, v11, v248, vcc
	v_cndmask_b32_e32 v10, v10, v248, vcc
	v_cndmask_b32_e32 v9, v9, v248, vcc
	v_cndmask_b32_e32 v8, v8, v248, vcc
	v_cndmask_b32_e32 v7, v7, v248, vcc
	v_cndmask_b32_e32 v6, v6, v248, vcc
	v_cndmask_b32_e32 v5, v5, v248, vcc
	v_cndmask_b32_e32 v4, v4, v248, vcc
	v_cndmask_b32_e32 v3, v3, v248, vcc
	v_cndmask_b32_e32 v2, v2, v248, vcc
